# P0 x conversion made batch-local (XCD b converts batch b rows, so xb lands in the consumer XCD's L2)
# baseline (speedup 1.0000x reference)
; DI unsigned cvt_pk(float lo, float hi) { const f32x2 v = {lo, hi}; return __builtin_bit_cast(unsigned, __builtin_convertvector(v, bf16v2)); }
; DI void p0_prologue(const Params& P, LAS unsigned char* lds) {
;     ...
;         for (int row0 = bid * 8 + wid; row0 < NTOK; row0 += 2 * G * 8) {
;             const int row1 = row0 + G * 8; const bool has1 = row1 < NTOK;
;             const f32x4* xr0 = (const f32x4*)(P.x + (size_t)row0 * DM);
;             const f32x4* xr1 = (const f32x4*)(P.x + (size_t)(has1 ? row1 : row0) * DM);
;             f32x4 v0[4], v1[4];
; #pragma unroll
;             for (int i = 0; i < 4; ++i) { v0[i] = xr0[lane + 64 * i]; v1[i] = xr1[lane + 64 * i]; }
;             float s0 = 0.f, s1 = 0.f;
; #pragma unroll
;             for (int i = 0; i < 4; ++i) {
;                 s0 += v0[i][0] * v0[i][0] + v0[i][1] * v0[i][1] + v0[i][2] * v0[i][2] + v0[i][3] * v0[i][3];
;                 s1 += v1[i][0] * v1[i][0] + v1[i][1] * v1[i][1] + v1[i][2] * v1[i][2] + v1[i][3] * v1[i][3];
;                 u32x2 w; w.x = cvt_pk(v0[i][0], v0[i][1]); w.y = cvt_pk(v0[i][2], v0[i][3]);
;                 *(u32x2*)(xb + (size_t)row0 * DM + 4 * (lane + 64 * i)) = w;
;                 if (has1) { u32x2 w1; w1.x = cvt_pk(v1[i][0], v1[i][1]); w1.y = cvt_pk(v1[i][2], v1[i][3]); *(u32x2*)(xb + (size_t)row1 * DM + 4 * (lane + 64 * i)) = w1; }
.LBB0_5:
	s_or_b64 exec, exec, s[0:1]
	s_add_u32 s26, s50, 0x2000000
	s_addc_u32 s27, s51, 0
	s_add_u32 s8, s50, 0x1200000
	v_lshrrev_b32_e32 v2, 6, v234
	s_addc_u32 s9, s51, 0
	s_lshl_b32 s94, s3, 3
	v_add_u32_e32 v72, s94, v2
	s_mov_b32 s2, 0x8000
	v_and_b32_e32 v1, 63, v234
	v_cmp_gt_i32_e32 vcc, s2, v72
	s_lshl_b32 s70, s24, 3
	v_mov_b32_e32 v35, 0
	v_mbcnt_lo_u32_b32 v224, -1, 0
	s_and_saveexec_b64 s[10:11], vcc
	s_cbranch_execz .LBB0_19
	v_mbcnt_hi_u32_b32 v2, -1, v224
	v_and_b32_e32 v3, 64, v2
	v_add_u32_e32 v3, 64, v3
	v_xor_b32_e32 v4, 32, v2
	v_cmp_lt_i32_e64 s[0:1], v4, v3
	v_lshlrev_b32_e32 v34, 4, v1
	v_lshl_add_u64 v[38:39], s[52:53], 0, v[34:35]
	v_cndmask_b32_e64 v4, v2, v4, s[0:1]
	v_lshlrev_b32_e32 v37, 2, v4
	v_xor_b32_e32 v4, 16, v2
	v_cmp_lt_i32_e64 s[0:1], v4, v3
	v_lshlrev_b32_e32 v34, 3, v1
	v_lshlrev_b32_e32 v36, 2, v1
	v_cndmask_b32_e64 v4, v2, v4, s[0:1]
	v_lshlrev_b32_e32 v50, 2, v4
	v_xor_b32_e32 v4, 8, v2
	v_cmp_lt_i32_e64 s[0:1], v4, v3
	v_cmp_eq_u32_e32 vcc, 0, v1
	v_lshl_add_u64 v[40:41], s[26:27], 0, v[34:35]
	v_cndmask_b32_e64 v4, v2, v4, s[0:1]
	v_lshlrev_b32_e32 v51, 2, v4
	v_xor_b32_e32 v4, 4, v2
	v_cmp_lt_i32_e64 s[0:1], v4, v3
	s_ashr_i32 s71, s70, 31
	s_mov_b64 s[12:13], 0
	v_cndmask_b32_e64 v4, v2, v4, s[0:1]
	v_lshlrev_b32_e32 v52, 2, v4
	v_xor_b32_e32 v4, 2, v2
	v_cmp_lt_i32_e64 s[0:1], v4, v3
	v_mov_b32_e32 v55, 0x358637bd
	s_mov_b32 s6, 0x800000
	v_cndmask_b32_e64 v4, v2, v4, s[0:1]
	v_lshlrev_b32_e32 v53, 2, v4
	v_xor_b32_e32 v4, 1, v2
	v_cmp_lt_i32_e64 s[0:1], v4, v3
	v_cndmask_b32_e64 v2, v2, v4, s[0:1]
	v_lshlrev_b32_e32 v54, 2, v2
	s_and_b32 s7, s3, 7
	s_lshl_b32 s7, s7, 12
	s_lshr_b32 s0, s3, 3
	s_lshl_b32 s0, s0, 3
	s_add_i32 s0, s0, s7
	v_lshrrev_b32_e32 v44, 6, v234
	v_add_u32_e32 v44, s0, v44
	s_or_b32 s7, s7, 0xfff
	s_branch .LBB0_8
.LBB0_7:
	s_or_b64 exec, exec, s[14:15]
	v_add_u32_e32 v44, 0x100, v42
	v_cmp_lt_i32_e64 s[0:1], s7, v44
	s_or_b64 s[12:13], s[0:1], s[12:13]
	s_andn2_b64 exec, exec, s[12:13]
	s_cbranch_execz .LBB0_19
.LBB0_8:
	v_add_u32_e32 v42, 0x100, v44
	v_cmp_gt_i32_e64 s[0:1], s2, v42
	v_ashrrev_i32_e32 v45, 31, v44
	s_waitcnt lgkmcnt(0)
	v_lshlrev_b64 v[4:5], 12, v[44:45]
	v_cndmask_b32_e64 v2, v44, v42, s[0:1]
	v_ashrrev_i32_e32 v3, 31, v2
	v_lshlrev_b64 v[2:3], 12, v[2:3]
	v_lshl_add_u64 v[4:5], v[38:39], 0, v[4:5]
	v_lshl_add_u64 v[2:3], v[38:39], 0, v[2:3]
	global_load_dwordx4 v[30:33], v[4:5], off nt
	global_load_dwordx4 v[22:25], v[4:5], off offset:1024 nt
	global_load_dwordx4 v[26:29], v[2:3], off nt
	global_load_dwordx4 v[18:21], v[2:3], off offset:1024 nt
	global_load_dwordx4 v[14:17], v[4:5], off offset:2048 nt
	global_load_dwordx4 v[6:9], v[4:5], off offset:3072 nt
	global_load_dwordx4 v[10:13], v[2:3], off offset:2048 nt
	s_nop 0
	global_load_dwordx4 v[2:5], v[2:3], off offset:3072 nt
	v_ashrrev_i32_e32 v43, 31, v42
	v_lshlrev_b64 v[46:47], 11, v[44:45]
	v_lshlrev_b64 v[56:57], 11, v[42:43]
	v_lshl_add_u64 v[48:49], v[40:41], 0, v[46:47]
	v_lshl_add_u64 v[46:47], s[26:27], 0, v[56:57]
	v_lshlrev_b32_e32 v34, 1, v36
	s_waitcnt vmcnt(7)
	v_cvt_pk_bf16_f32 v56, v30, v31
	v_cvt_pk_bf16_f32 v57, v32, v33
	global_store_dwordx2 v[48:49], v[56:57], off
	s_and_saveexec_b64 s[4:5], s[0:1]
	s_cbranch_execz .LBB0_10
	s_waitcnt vmcnt(6)
	v_cvt_pk_bf16_f32 v56, v26, v27
	v_cvt_pk_bf16_f32 v57, v28, v29
	v_lshl_add_u64 v[58:59], v[46:47], 0, v[34:35]
	global_store_dwordx2 v[58:59], v[56:57], off

; DI unsigned cvt_pk(float lo, float hi) { const f32x2 v = {lo, hi}; return __builtin_bit_cast(unsigned, __builtin_convertvector(v, bf16v2)); }
; DI void p0_prologue(const Params& P, LAS unsigned char* lds) {
;     ...
;                 s0 += v0[i][0] * v0[i][0] + v0[i][1] * v0[i][1] + v0[i][2] * v0[i][2] + v0[i][3] * v0[i][3];
;                 s1 += v1[i][0] * v1[i][0] + v1[i][1] * v1[i][1] + v1[i][2] * v1[i][2] + v1[i][3] * v1[i][3];
;                 u32x2 w; w.x = cvt_pk(v0[i][0], v0[i][1]); w.y = cvt_pk(v0[i][2], v0[i][3]);
;                 *(u32x2*)(xb + (size_t)row0 * DM + 4 * (lane + 64 * i)) = w;
;                 if (has1) { u32x2 w1; w1.x = cvt_pk(v1[i][0], v1[i][1]); w1.y = cvt_pk(v1[i][2], v1[i][3]); *(u32x2*)(xb + (size_t)row1 * DM + 4 * (lane + 64 * i)) = w1; }
;             }
; #pragma unroll
;             for (int o = 32; o >= 1; o >>= 1) { s0 += __shfl_xor(s0, o); s1 += __shfl_xor(s1, o); }
;             if (lane == 0) { rstd[row0] = rsqrtf(s0 * (1.0f / DM) + NORM_EPS); if (has1) rstd[row1] = rsqrtf(s1 * (1.0f / DM) + NORM_EPS); }
.LBB0_16:
	s_or_b64 exec, exec, s[4:5]
	v_mul_f32_e32 v31, v31, v31
	v_mul_f32_e32 v27, v27, v27
	v_mul_f32_e32 v23, v23, v23
	v_mul_f32_e32 v19, v19, v19
	v_fmac_f32_e32 v31, v30, v30
	v_fmac_f32_e32 v27, v26, v26
	v_fmac_f32_e32 v23, v22, v22
	v_fmac_f32_e32 v19, v18, v18
	v_mul_f32_e32 v15, v15, v15
	s_waitcnt vmcnt(5)
	v_mul_f32_e32 v11, v11, v11
	v_fmac_f32_e32 v31, v32, v32
	v_fmac_f32_e32 v27, v28, v28
	v_fmac_f32_e32 v23, v24, v24
	v_fmac_f32_e32 v19, v20, v20
	v_fmac_f32_e32 v15, v14, v14
	v_fmac_f32_e32 v11, v10, v10
	v_mul_f32_e32 v7, v7, v7
	s_waitcnt vmcnt(4)
	v_mul_f32_e32 v3, v3, v3
	v_fmac_f32_e32 v31, v33, v33
	v_fmac_f32_e32 v27, v29, v29
	v_fmac_f32_e32 v23, v25, v25
	v_fmac_f32_e32 v19, v21, v21
	v_fmac_f32_e32 v15, v16, v16
	v_fmac_f32_e32 v11, v12, v12
	v_fmac_f32_e32 v7, v6, v6
	v_fmac_f32_e32 v3, v2, v2
	v_add_f32_e32 v22, v31, v23
	v_add_f32_e32 v18, v27, v19
	v_fmac_f32_e32 v15, v17, v17
	v_fmac_f32_e32 v11, v13, v13
	v_fmac_f32_e32 v7, v8, v8
	v_fmac_f32_e32 v3, v4, v4
	v_add_f32_e32 v14, v22, v15
	v_add_f32_e32 v10, v18, v11
	v_fmac_f32_e32 v7, v9, v9
	v_fmac_f32_e32 v3, v5, v5
	v_add_f32_e32 v6, v14, v7
	v_add_f32_e32 v2, v10, v3
	ds_bpermute_b32 v3, v37, v6
	ds_bpermute_b32 v4, v37, v2
	s_waitcnt lgkmcnt(1)
	v_add_f32_e32 v3, v6, v3
	s_waitcnt lgkmcnt(0)
	v_add_f32_e32 v2, v2, v4
	ds_bpermute_b32 v4, v50, v3
	ds_bpermute_b32 v5, v50, v2
	s_waitcnt lgkmcnt(1)
	v_add_f32_e32 v3, v3, v4
	s_waitcnt lgkmcnt(0)
	v_add_f32_e32 v2, v2, v5
	ds_bpermute_b32 v4, v51, v3
	ds_bpermute_b32 v5, v51, v2
	s_waitcnt lgkmcnt(1)
	v_add_f32_e32 v3, v3, v4
	s_waitcnt lgkmcnt(0)
	v_add_f32_e32 v2, v2, v5
	ds_bpermute_b32 v4, v52, v3
	ds_bpermute_b32 v5, v52, v2
	s_waitcnt lgkmcnt(1)
	v_add_f32_e32 v3, v3, v4
	s_waitcnt lgkmcnt(0)
	v_add_f32_e32 v4, v2, v5
	ds_bpermute_b32 v2, v53, v3
	ds_bpermute_b32 v5, v53, v4
	s_waitcnt lgkmcnt(1)
	v_add_f32_e32 v2, v3, v2
	s_waitcnt lgkmcnt(0)
	v_add_f32_e32 v4, v4, v5
	ds_bpermute_b32 v3, v54, v2
	ds_bpermute_b32 v5, v54, v4
	s_and_saveexec_b64 s[14:15], vcc
	s_cbranch_execz .LBB0_7
	s_waitcnt lgkmcnt(1)
	v_add_f32_e32 v2, v2, v3
	v_fmamk_f32 v2, v2, 0x3a800000, v55
	v_mul_f32_e32 v3, 0x4b800000, v2
	v_cmp_gt_f32_e64 s[4:5], s6, v2
	s_nop 1
	v_cndmask_b32_e64 v2, v2, v3, s[4:5]
	v_rsq_f32_e32 v2, v2
	s_nop 0
	v_mul_f32_e32 v3, 0x45800000, v2
	v_cndmask_b32_e64 v6, v2, v3, s[4:5]
	v_lshl_add_u64 v[2:3], v[44:45], 2, s[8:9]
	global_store_dword v[2:3], v6, off
	s_and_b64 exec, exec, s[0:1]
	s_cbranch_execz .LBB0_7
	s_movk_i32 s4, 0x400
	v_add_co_u32_e64 v2, s[0:1], s4, v2
	s_nop 1
	v_addc_co_u32_e64 v3, s[0:1], 0, v3, s[0:1]
	s_waitcnt lgkmcnt(0)
	v_add_f32_e32 v4, v4, v5
	v_fmamk_f32 v4, v4, 0x3a800000, v55
	v_mul_f32_e32 v5, 0x4b800000, v4
	v_cmp_gt_f32_e64 s[0:1], s6, v4
	s_nop 1
	v_cndmask_b32_e64 v4, v4, v5, s[0:1]
	v_rsq_f32_e32 v4, v4
	s_nop 0
	v_mul_f32_e32 v5, 0x45800000, v4
	v_cndmask_b32_e64 v4, v4, v5, s[0:1]
	global_store_dword v[2:3], v4, off
	s_branch .LBB0_7
